# grid barrier: non-leader workgroups poll the cross-XCD release generation directly (one hop less on the release path)
# baseline (speedup 1.0000x reference)
.LBB0_285:
	s_or_b64 exec, exec, s[8:9]
	v_cvt_f32_u32_e32 v4, v2
	s_waitcnt vmcnt(0)
	v_readfirstlane_b32 s4, v3
	v_sub_u32_e32 v3, 0, v2
	v_rcp_iflag_f32_e32 v4, v4
	v_add_u32_e32 v5, s4, v1
	v_mul_f32_e32 v4, 0x4f7ffffe, v4
	v_cvt_u32_f32_e32 v4, v4
	v_mul_lo_u32 v1, v3, v4
	v_mul_hi_u32 v1, v4, v1
	v_add_u32_e32 v1, v4, v1
	v_mul_hi_u32 v1, v5, v1
	v_mul_lo_u32 v3, v1, v2
	v_sub_u32_e32 v3, v5, v3
	v_add_u32_e32 v4, 1, v1
	v_cmp_ge_u32_e32 vcc, v3, v2
	s_nop 1
	v_cndmask_b32_e32 v1, v1, v4, vcc
	v_sub_u32_e32 v4, v3, v2
	v_cndmask_b32_e32 v3, v3, v4, vcc
	v_add_u32_e32 v4, 1, v1
	v_cmp_ge_u32_e32 vcc, v3, v2
	v_add_u32_e32 v3, 1, v5
	s_nop 0
	v_cndmask_b32_e32 v1, v1, v4, vcc
	v_mul_lo_u32 v4, v2, v1
	v_add_u32_e32 v2, v4, v2
	v_cmp_ne_u32_e32 vcc, v3, v2
	s_and_saveexec_b64 s[4:5], vcc
	s_xor_b64 s[4:5], exec, s[4:5]
	s_cbranch_execz .LBB0_299
	s_waitcnt lgkmcnt(0)
	s_add_u32 s20, s38, 0x3500
	s_addc_u32 s21, s39, 0
	v_mov_b32_e32 v0, 0
	global_load_dword v0, v0, s[20:21] sc1
	s_waitcnt vmcnt(0)
	v_cmp_eq_u32_e32 vcc, v0, v1
	s_and_saveexec_b64 s[8:9], vcc
	s_cbranch_execz .LBB0_298
	s_add_u32 s10, s92, 0x2ad81a00
	s_addc_u32 s11, s93, 0
	s_mov_b32 s14, 1
	s_mov_b64 s[22:23], 0
	v_mov_b32_e32 v0, 0
	s_branch .LBB0_289

.LBB0_613:
	s_or_b64 exec, exec, s[4:5]
	v_cvt_f32_u32_e32 v5, v3
	s_waitcnt vmcnt(0)
	v_readfirstlane_b32 s4, v4
	v_sub_u32_e32 v4, 0, v3
	v_rcp_iflag_f32_e32 v5, v5
	v_add_u32_e32 v6, s4, v0
	v_mul_f32_e32 v5, 0x4f7ffffe, v5
	v_cvt_u32_f32_e32 v5, v5
	v_mul_lo_u32 v0, v4, v5
	v_mul_hi_u32 v0, v5, v0
	v_add_u32_e32 v0, v5, v0
	v_mul_hi_u32 v0, v6, v0
	v_mul_lo_u32 v4, v0, v3
	v_sub_u32_e32 v4, v6, v4
	v_add_u32_e32 v5, 1, v0
	v_cmp_ge_u32_e32 vcc, v4, v3
	s_nop 1
	v_cndmask_b32_e32 v0, v0, v5, vcc
	v_sub_u32_e32 v5, v4, v3
	v_cndmask_b32_e32 v4, v4, v5, vcc
	v_add_u32_e32 v5, 1, v0
	v_cmp_ge_u32_e32 vcc, v4, v3
	v_add_u32_e32 v4, 1, v6
	s_nop 0
	v_cndmask_b32_e32 v0, v0, v5, vcc
	v_mul_lo_u32 v5, v3, v0
	v_add_u32_e32 v3, v5, v3
	v_cmp_ne_u32_e32 vcc, v4, v3
	s_and_saveexec_b64 s[4:5], vcc
	s_xor_b64 s[4:5], exec, s[4:5]
	s_cbranch_execz .LBB0_627
	v_readlane_b32 s6, v253, 1
	v_readlane_b32 s7, v253, 2
	s_waitcnt lgkmcnt(0)
	s_nop 3
	global_load_dword v2, v1, s[6:7] sc1
	s_waitcnt vmcnt(0)
	v_cmp_eq_u32_e32 vcc, v2, v0
	s_and_saveexec_b64 s[6:7], vcc
	s_cbranch_execz .LBB0_626
	s_mov_b32 s18, 1
	s_mov_b64 s[8:9], 0
	s_branch .LBB0_617

.LBB0_1618:
	s_or_b64 exec, exec, s[8:9]
	v_cvt_f32_u32_e32 v5, v3
	s_waitcnt vmcnt(0)
	v_readfirstlane_b32 s8, v4
	v_sub_u32_e32 v4, 0, v3
	v_rcp_iflag_f32_e32 v5, v5
	v_add_u32_e32 v6, s8, v0
	v_mul_f32_e32 v5, 0x4f7ffffe, v5
	v_cvt_u32_f32_e32 v5, v5
	v_mul_lo_u32 v0, v4, v5
	v_mul_hi_u32 v0, v5, v0
	v_add_u32_e32 v0, v5, v0
	v_mul_hi_u32 v0, v6, v0
	v_mul_lo_u32 v4, v0, v3
	v_sub_u32_e32 v4, v6, v4
	v_add_u32_e32 v5, 1, v0
	v_cmp_ge_u32_e32 vcc, v4, v3
	s_nop 1
	v_cndmask_b32_e32 v0, v0, v5, vcc
	v_sub_u32_e32 v5, v4, v3
	v_cndmask_b32_e32 v4, v4, v5, vcc
	v_add_u32_e32 v5, 1, v0
	v_cmp_ge_u32_e32 vcc, v4, v3
	v_add_u32_e32 v4, 1, v6
	s_nop 0
	v_cndmask_b32_e32 v0, v0, v5, vcc
	v_mul_lo_u32 v5, v3, v0
	v_add_u32_e32 v3, v5, v3
	v_cmp_ne_u32_e32 vcc, v4, v3
	s_and_saveexec_b64 s[8:9], vcc
	s_xor_b64 s[8:9], exec, s[8:9]
	s_cbranch_execz .LBB0_1632
	v_readlane_b32 s18, v253, 1
	v_readlane_b32 s19, v253, 2
	s_waitcnt lgkmcnt(0)
	s_nop 3
	global_load_dword v2, v1, s[18:19] sc1
	s_waitcnt vmcnt(0)
	v_cmp_eq_u32_e32 vcc, v2, v0
	s_and_saveexec_b64 s[30:31], vcc
	s_cbranch_execz .LBB0_1631
	s_mov_b32 s18, 1
	s_mov_b64 s[36:37], 0
	s_branch .LBB0_1622

.LBB0_1930:
	s_or_b64 exec, exec, s[2:3]
	v_cvt_f32_u32_e32 v5, v3
	s_waitcnt vmcnt(0)
	v_readfirstlane_b32 s2, v4
	v_sub_u32_e32 v4, 0, v3
	v_rcp_iflag_f32_e32 v5, v5
	v_add_u32_e32 v6, s2, v0
	v_mul_f32_e32 v5, 0x4f7ffffe, v5
	v_cvt_u32_f32_e32 v5, v5
	v_mul_lo_u32 v0, v4, v5
	v_mul_hi_u32 v0, v5, v0
	v_add_u32_e32 v0, v5, v0
	v_mul_hi_u32 v0, v6, v0
	v_mul_lo_u32 v4, v0, v3
	v_sub_u32_e32 v4, v6, v4
	v_add_u32_e32 v5, 1, v0
	v_cmp_ge_u32_e32 vcc, v4, v3
	s_nop 1
	v_cndmask_b32_e32 v0, v0, v5, vcc
	v_sub_u32_e32 v5, v4, v3
	v_cndmask_b32_e32 v4, v4, v5, vcc
	v_add_u32_e32 v5, 1, v0
	v_cmp_ge_u32_e32 vcc, v4, v3
	v_add_u32_e32 v4, 1, v6
	s_nop 0
	v_cndmask_b32_e32 v0, v0, v5, vcc
	v_mul_lo_u32 v5, v3, v0
	v_add_u32_e32 v3, v5, v3
	v_cmp_ne_u32_e32 vcc, v4, v3
	s_and_saveexec_b64 s[2:3], vcc
	s_xor_b64 s[2:3], exec, s[2:3]
	s_cbranch_execz .LBB0_1944
	v_readlane_b32 s4, v253, 1
	v_readlane_b32 s5, v253, 2
	s_waitcnt lgkmcnt(0)
	s_nop 3
	global_load_dword v2, v1, s[4:5] sc1
	s_waitcnt vmcnt(0)
	v_cmp_eq_u32_e32 vcc, v2, v0
	s_and_saveexec_b64 s[4:5], vcc
	s_cbranch_execz .LBB0_1943
	s_mov_b32 s17, 1
	s_mov_b64 s[6:7], 0
	s_branch .LBB0_1934
